# grid barrier: leader no longer bumps (and waits for) the per-XCD generation word nobody polls any more
# baseline (speedup 1.0000x reference)
; __device__ __forceinline__ unsigned xb_ld(unsigned* p)              { return __hip_atomic_load(p, __ATOMIC_RELAXED, __HIP_MEMORY_SCOPE_AGENT); }
; __device__ __forceinline__ unsigned xb_add(unsigned* p, unsigned v) { return __hip_atomic_fetch_add(p, v, __ATOMIC_RELAXED, __HIP_MEMORY_SCOPE_AGENT); }
; #define XB_SPIN(cond, bar) do { unsigned _sp = 0; while (cond) { __builtin_amdgcn_s_sleep(1); \
;     if ((++_sp & 255u) == 0u) { if (xb_ld(&(bar)[XB_TMO])) break; if (_sp > XB_SPIN_CAP) { atomicAdd(&(bar)[XB_TMO], 1u); break; } } } } while (0)
; __device__ __forceinline__ void xcd_barrier(const XcdBarrier& b) {
;     ...
;             __builtin_amdgcn_fence(__ATOMIC_RELEASE, "agent");
;             asm volatile("s_waitcnt vmcnt(0)" ::: "memory");
;             const unsigned og = xb_add(&bar[XB_TOP], 1u);
;             const unsigned tg = og / nx;
;             if (og + 1u == (tg + 1u) * nx) xb_add(&bar[XB_TOPGEN], 1u);
;             else XB_SPIN(xb_ld(&bar[XB_TOPGEN]) == tg, bar);
;             __builtin_amdgcn_fence(__ATOMIC_ACQUIRE, "agent");
;             xb_add(&bar[XB_XGEN(b.x)], 1u);
;             asm volatile("s_waitcnt vmcnt(0)" ::: "memory");
.LBB0_267:
	s_or_b64 exec, exec, s[4:5]
	v_mov_b32_e32 v0, 0x2000
	v_mov_b32_e32 v1, 1
	s_waitcnt vmcnt(0)
	buffer_inv sc1
	s_nop 0
	s_nop 0
	s_waitcnt vmcnt(0)
